# attention epilogue rewritten by hand: same math, output staged through a private per-wave LDS tile and written with 8 global_store_dwordx4 instead of 64 2-byte stores per lane; rest as v69
# baseline (speedup 1.0000x reference)
; __device__ __forceinline__ unsigned f2bf(float f) { unsigned u = __builtin_bit_cast(unsigned, f); return (u + 0x7fffu + ((u >> 16) & 1u)) >> 16; }
; __device__ __forceinline__ int crow(int r, int hi) { return (r & 3) + 8 * (r >> 2) + 4 * hi; }
; __device__ __forceinline__ void attn_unit(const bf16* QKVb, bf16* AMIXb, const float* sinkp, const float* relb, int u, LAS unsigned char* lds, int tid, int lane, int wave, int& tab_key) {
;     ...
;     if (hi == 0) wsc[r32] = l_reg; asm volatile("s_waitcnt lgkmcnt(0)" ::: "memory");
;     bf16* Ow = AMIXb + (size_t)(q0 + qa * 32) * D + head * 128 + r32;
; #pragma unroll
;     for (int r = 0; r < 16; ++r) { const int orow = crow(r, hi); const float rl = __builtin_amdgcn_rcpf(wsc[orow]);
; #pragma unroll
;         for (int d0 = 0; d0 < 4; ++d0) Ow[(size_t)orow * D + d0 * 32] = (bf16)f2bf(o[d0][r] * rl); }
.LBB0_458:
	s_or_b64 exec, exec, s[46:47]
	s_ashr_i32 s45, s44, 31
	s_lshl_b64 s[40:41], s[44:45], 12
	s_add_u32 s30, s52, s40
	s_addc_u32 s41, s53, s41
	s_lshl_b32 s40, s71, 1
	s_add_u32 s40, s30, s40
	s_addc_u32 s41, s41, 0
	v_lshlrev_b32_e32 v0, 1, v179
	s_waitcnt lgkmcnt(0)
	v_add_u32_e32 v6, s1, v165
	ds_read_b128 v[2:5], v6
	ds_read_b128 v[8:11], v6 offset:32
	s_sub_u32 s30, s1, 0x10000
	s_lshl_b32 s30, s30, 5
	s_add_u32 s30, s30, 0x12000
	v_lshl_add_u32 v7, v178, 10, v0
	v_add_u32_e32 v7, s30, v7
	s_waitcnt lgkmcnt(0)
	v_rcp_f32_e32 v2, v2
	v_rcp_f32_e32 v3, v3
	v_rcp_f32_e32 v4, v4
	v_rcp_f32_e32 v5, v5
	v_rcp_f32_e32 v8, v8
	v_rcp_f32_e32 v9, v9
	v_rcp_f32_e32 v10, v10
	v_rcp_f32_e32 v11, v11
	s_nop 0
	v_mul_f32_e32 v64, v64, v2
	v_bfe_u32 v12, v64, 16, 1
	v_add3_u32 v64, v64, v12, s66
	ds_write_b16_d16_hi v7, v64 offset:0
	v_mul_f32_e32 v48, v48, v2
	v_bfe_u32 v13, v48, 16, 1
	v_add3_u32 v48, v48, v13, s66
	ds_write_b16_d16_hi v7, v48 offset:64
	v_mul_f32_e32 v32, v32, v2
	v_bfe_u32 v0, v32, 16, 1
	v_add3_u32 v32, v32, v0, s66
	ds_write_b16_d16_hi v7, v32 offset:128
	v_mul_f32_e32 v16, v16, v2
	v_bfe_u32 v12, v16, 16, 1
	v_add3_u32 v16, v16, v12, s66
	ds_write_b16_d16_hi v7, v16 offset:192
	v_mul_f32_e32 v65, v65, v3
	v_bfe_u32 v13, v65, 16, 1
	v_add3_u32 v65, v65, v13, s66
	ds_write_b16_d16_hi v7, v65 offset:256
	v_mul_f32_e32 v49, v49, v3
	v_bfe_u32 v0, v49, 16, 1
	v_add3_u32 v49, v49, v0, s66
	ds_write_b16_d16_hi v7, v49 offset:320
	v_mul_f32_e32 v33, v33, v3
	v_bfe_u32 v12, v33, 16, 1
	v_add3_u32 v33, v33, v12, s66
	ds_write_b16_d16_hi v7, v33 offset:384
	v_mul_f32_e32 v17, v17, v3
	v_bfe_u32 v13, v17, 16, 1
	v_add3_u32 v17, v17, v13, s66
	ds_write_b16_d16_hi v7, v17 offset:448
	v_mul_f32_e32 v66, v66, v4
	v_bfe_u32 v0, v66, 16, 1
	v_add3_u32 v66, v66, v0, s66
	ds_write_b16_d16_hi v7, v66 offset:512
	v_mul_f32_e32 v50, v50, v4
	v_bfe_u32 v12, v50, 16, 1
	v_add3_u32 v50, v50, v12, s66
	ds_write_b16_d16_hi v7, v50 offset:576
	v_mul_f32_e32 v34, v34, v4
	v_bfe_u32 v13, v34, 16, 1
	v_add3_u32 v34, v34, v13, s66
	ds_write_b16_d16_hi v7, v34 offset:640
	v_mul_f32_e32 v18, v18, v4
	v_bfe_u32 v0, v18, 16, 1
	v_add3_u32 v18, v18, v0, s66
	ds_write_b16_d16_hi v7, v18 offset:704
	v_mul_f32_e32 v67, v67, v5
	v_bfe_u32 v12, v67, 16, 1
	v_add3_u32 v67, v67, v12, s66
	ds_write_b16_d16_hi v7, v67 offset:768
	v_mul_f32_e32 v51, v51, v5
	v_bfe_u32 v13, v51, 16, 1
	v_add3_u32 v51, v51, v13, s66
	ds_write_b16_d16_hi v7, v51 offset:832
	v_mul_f32_e32 v35, v35, v5
	v_bfe_u32 v0, v35, 16, 1
	v_add3_u32 v35, v35, v0, s66
	ds_write_b16_d16_hi v7, v35 offset:896
	v_mul_f32_e32 v19, v19, v5
	v_bfe_u32 v12, v19, 16, 1
	v_add3_u32 v19, v19, v12, s66
	ds_write_b16_d16_hi v7, v19 offset:960
	v_mul_f32_e32 v68, v68, v8
	v_bfe_u32 v13, v68, 16, 1
	v_add3_u32 v68, v68, v13, s66
	ds_write_b16_d16_hi v7, v68 offset:2048
	v_mul_f32_e32 v52, v52, v8
	v_bfe_u32 v0, v52, 16, 1
	v_add3_u32 v52, v52, v0, s66
	ds_write_b16_d16_hi v7, v52 offset:2112
	v_mul_f32_e32 v36, v36, v8
	v_bfe_u32 v12, v36, 16, 1
	v_add3_u32 v36, v36, v12, s66
	ds_write_b16_d16_hi v7, v36 offset:2176
	v_mul_f32_e32 v20, v20, v8
	v_bfe_u32 v13, v20, 16, 1
	v_add3_u32 v20, v20, v13, s66
	ds_write_b16_d16_hi v7, v20 offset:2240
	v_mul_f32_e32 v69, v69, v9
	v_bfe_u32 v0, v69, 16, 1
	v_add3_u32 v69, v69, v0, s66
	ds_write_b16_d16_hi v7, v69 offset:2304
	v_mul_f32_e32 v53, v53, v9
	v_bfe_u32 v12, v53, 16, 1
	v_add3_u32 v53, v53, v12, s66
	ds_write_b16_d16_hi v7, v53 offset:2368
	v_mul_f32_e32 v37, v37, v9
	v_bfe_u32 v13, v37, 16, 1
	v_add3_u32 v37, v37, v13, s66
	ds_write_b16_d16_hi v7, v37 offset:2432
	v_mul_f32_e32 v21, v21, v9
	v_bfe_u32 v0, v21, 16, 1
	v_add3_u32 v21, v21, v0, s66
	ds_write_b16_d16_hi v7, v21 offset:2496
	v_mul_f32_e32 v70, v70, v10
	v_bfe_u32 v12, v70, 16, 1
	v_add3_u32 v70, v70, v12, s66
	ds_write_b16_d16_hi v7, v70 offset:2560
	v_mul_f32_e32 v54, v54, v10
	v_bfe_u32 v13, v54, 16, 1
	v_add3_u32 v54, v54, v13, s66
	ds_write_b16_d16_hi v7, v54 offset:2624
	v_mul_f32_e32 v38, v38, v10
	v_bfe_u32 v0, v38, 16, 1
	v_add3_u32 v38, v38, v0, s66
	ds_write_b16_d16_hi v7, v38 offset:2688
	v_mul_f32_e32 v22, v22, v10
	v_bfe_u32 v12, v22, 16, 1
	v_add3_u32 v22, v22, v12, s66
	ds_write_b16_d16_hi v7, v22 offset:2752
	v_mul_f32_e32 v71, v71, v11
	v_bfe_u32 v13, v71, 16, 1
	v_add3_u32 v71, v71, v13, s66
	ds_write_b16_d16_hi v7, v71 offset:2816
	v_mul_f32_e32 v55, v55, v11
	v_bfe_u32 v0, v55, 16, 1
	v_add3_u32 v55, v55, v0, s66
	ds_write_b16_d16_hi v7, v55 offset:2880
	v_mul_f32_e32 v39, v39, v11
	v_bfe_u32 v12, v39, 16, 1
	v_add3_u32 v39, v39, v12, s66
	ds_write_b16_d16_hi v7, v39 offset:2944
	v_mul_f32_e32 v23, v23, v11
	v_bfe_u32 v13, v23, 16, 1
	v_add3_u32 v23, v23, v13, s66
	ds_write_b16_d16_hi v7, v23 offset:3008
	ds_read_b128 v[2:5], v6 offset:64
	ds_read_b128 v[8:11], v6 offset:96
	s_waitcnt lgkmcnt(0)
; __device__ __forceinline__ unsigned f2bf(float f) { unsigned u = __builtin_bit_cast(unsigned, f); return (u + 0x7fffu + ((u >> 16) & 1u)) >> 16; }
; __device__ __forceinline__ int crow(int r, int hi) { return (r & 3) + 8 * (r >> 2) + 4 * hi; }
; __device__ __forceinline__ void attn_unit(const bf16* QKVb, bf16* AMIXb, const float* sinkp, const float* relb, int u, LAS unsigned char* lds, int tid, int lane, int wave, int& tab_key) {
;     ...
;     for (int r = 0; r < 16; ++r) { const int orow = crow(r, hi); const float rl = __builtin_amdgcn_rcpf(wsc[orow]);
; #pragma unroll
;         for (int d0 = 0; d0 < 4; ++d0) Ow[(size_t)orow * D + d0 * 32] = (bf16)f2bf(o[d0][r] * rl); }
;     asm volatile("s_waitcnt lgkmcnt(0)" ::: "memory");
; __global__ void __launch_bounds__(512, 2) fwd_kernel(Args args) {
;     ...
;                         for (int u = blockIdx.x; u < 1536; u += G) att::attn_unit(HB, AMIX, ka->in[I_SINK] + ib * 16, ka->in[I_RELB], u, lds, tid, lane, wave, tab_key);
	v_rcp_f32_e32 v2, v2
	v_rcp_f32_e32 v3, v3
	v_rcp_f32_e32 v4, v4
	v_rcp_f32_e32 v5, v5
	v_rcp_f32_e32 v8, v8
	v_rcp_f32_e32 v9, v9
	v_rcp_f32_e32 v10, v10
	v_rcp_f32_e32 v11, v11
	s_nop 0
	v_mul_f32_e32 v72, v72, v2
	v_bfe_u32 v0, v72, 16, 1
	v_add3_u32 v72, v72, v0, s66
	ds_write_b16_d16_hi v7, v72 offset:4096
	v_mul_f32_e32 v56, v56, v2
	v_bfe_u32 v12, v56, 16, 1
	v_add3_u32 v56, v56, v12, s66
	ds_write_b16_d16_hi v7, v56 offset:4160
	v_mul_f32_e32 v40, v40, v2
	v_bfe_u32 v13, v40, 16, 1
	v_add3_u32 v40, v40, v13, s66
	ds_write_b16_d16_hi v7, v40 offset:4224
	v_mul_f32_e32 v24, v24, v2
	v_bfe_u32 v0, v24, 16, 1
	v_add3_u32 v24, v24, v0, s66
	ds_write_b16_d16_hi v7, v24 offset:4288
	v_mul_f32_e32 v73, v73, v3
	v_bfe_u32 v12, v73, 16, 1
	v_add3_u32 v73, v73, v12, s66
	ds_write_b16_d16_hi v7, v73 offset:4352
	v_mul_f32_e32 v57, v57, v3
	v_bfe_u32 v13, v57, 16, 1
	v_add3_u32 v57, v57, v13, s66
	ds_write_b16_d16_hi v7, v57 offset:4416
	v_mul_f32_e32 v41, v41, v3
	v_bfe_u32 v0, v41, 16, 1
	v_add3_u32 v41, v41, v0, s66
	ds_write_b16_d16_hi v7, v41 offset:4480
	v_mul_f32_e32 v25, v25, v3
	v_bfe_u32 v12, v25, 16, 1
	v_add3_u32 v25, v25, v12, s66
	ds_write_b16_d16_hi v7, v25 offset:4544
	v_mul_f32_e32 v74, v74, v4
	v_bfe_u32 v13, v74, 16, 1
	v_add3_u32 v74, v74, v13, s66
	ds_write_b16_d16_hi v7, v74 offset:4608
	v_mul_f32_e32 v58, v58, v4
	v_bfe_u32 v0, v58, 16, 1
	v_add3_u32 v58, v58, v0, s66
	ds_write_b16_d16_hi v7, v58 offset:4672
	v_mul_f32_e32 v42, v42, v4
	v_bfe_u32 v12, v42, 16, 1
	v_add3_u32 v42, v42, v12, s66
	ds_write_b16_d16_hi v7, v42 offset:4736
	v_mul_f32_e32 v26, v26, v4
	v_bfe_u32 v13, v26, 16, 1
	v_add3_u32 v26, v26, v13, s66
	ds_write_b16_d16_hi v7, v26 offset:4800
	v_mul_f32_e32 v75, v75, v5
	v_bfe_u32 v0, v75, 16, 1
	v_add3_u32 v75, v75, v0, s66
	ds_write_b16_d16_hi v7, v75 offset:4864
	v_mul_f32_e32 v59, v59, v5
	v_bfe_u32 v12, v59, 16, 1
	v_add3_u32 v59, v59, v12, s66
	ds_write_b16_d16_hi v7, v59 offset:4928
	v_mul_f32_e32 v43, v43, v5
	v_bfe_u32 v13, v43, 16, 1
	v_add3_u32 v43, v43, v13, s66
	ds_write_b16_d16_hi v7, v43 offset:4992
	v_mul_f32_e32 v27, v27, v5
	v_bfe_u32 v0, v27, 16, 1
	v_add3_u32 v27, v27, v0, s66
	ds_write_b16_d16_hi v7, v27 offset:5056
	v_mul_f32_e32 v76, v76, v8
	v_bfe_u32 v12, v76, 16, 1
	v_add3_u32 v76, v76, v12, s66
	ds_write_b16_d16_hi v7, v76 offset:6144
	v_mul_f32_e32 v60, v60, v8
	v_bfe_u32 v13, v60, 16, 1
	v_add3_u32 v60, v60, v13, s66
	ds_write_b16_d16_hi v7, v60 offset:6208
	v_mul_f32_e32 v44, v44, v8
	v_bfe_u32 v0, v44, 16, 1
	v_add3_u32 v44, v44, v0, s66
	ds_write_b16_d16_hi v7, v44 offset:6272
	v_mul_f32_e32 v28, v28, v8
	v_bfe_u32 v12, v28, 16, 1
	v_add3_u32 v28, v28, v12, s66
	ds_write_b16_d16_hi v7, v28 offset:6336
	v_mul_f32_e32 v77, v77, v9
	v_bfe_u32 v13, v77, 16, 1
	v_add3_u32 v77, v77, v13, s66
	ds_write_b16_d16_hi v7, v77 offset:6400
	v_mul_f32_e32 v61, v61, v9
	v_bfe_u32 v0, v61, 16, 1
	v_add3_u32 v61, v61, v0, s66
	ds_write_b16_d16_hi v7, v61 offset:6464
	v_mul_f32_e32 v45, v45, v9
	v_bfe_u32 v12, v45, 16, 1
	v_add3_u32 v45, v45, v12, s66
	ds_write_b16_d16_hi v7, v45 offset:6528
	v_mul_f32_e32 v29, v29, v9
	v_bfe_u32 v13, v29, 16, 1
	v_add3_u32 v29, v29, v13, s66
	ds_write_b16_d16_hi v7, v29 offset:6592
	v_mul_f32_e32 v78, v78, v10
	v_bfe_u32 v0, v78, 16, 1
	v_add3_u32 v78, v78, v0, s66
	ds_write_b16_d16_hi v7, v78 offset:6656
	v_mul_f32_e32 v62, v62, v10
	v_bfe_u32 v12, v62, 16, 1
	v_add3_u32 v62, v62, v12, s66
	ds_write_b16_d16_hi v7, v62 offset:6720
	v_mul_f32_e32 v46, v46, v10
	v_bfe_u32 v13, v46, 16, 1
	v_add3_u32 v46, v46, v13, s66
	ds_write_b16_d16_hi v7, v46 offset:6784
	v_mul_f32_e32 v30, v30, v10
	v_bfe_u32 v0, v30, 16, 1
	v_add3_u32 v30, v30, v0, s66
	ds_write_b16_d16_hi v7, v30 offset:6848
	v_mul_f32_e32 v79, v79, v11
	v_bfe_u32 v12, v79, 16, 1
	v_add3_u32 v79, v79, v12, s66
	ds_write_b16_d16_hi v7, v79 offset:6912
	v_mul_f32_e32 v63, v63, v11
	v_bfe_u32 v13, v63, 16, 1
	v_add3_u32 v63, v63, v13, s66
	ds_write_b16_d16_hi v7, v63 offset:6976
	v_mul_f32_e32 v47, v47, v11
	v_bfe_u32 v0, v47, 16, 1
	v_add3_u32 v47, v47, v0, s66
	ds_write_b16_d16_hi v7, v47 offset:7040
	v_mul_f32_e32 v31, v31, v11
	v_bfe_u32 v12, v31, 16, 1
	v_add3_u32 v31, v31, v12, s66
	ds_write_b16_d16_hi v7, v31 offset:7104
	v_lshrrev_b32_e32 v2, 4, v170
	v_and_b32_e32 v3, 15, v170
	v_lshlrev_b32_e32 v3, 4, v3
	v_lshl_add_u32 v4, v2, 8, v3
	v_add_u32_e32 v4, s30, v4
	v_lshl_add_u32 v5, v2, 12, v3
	s_waitcnt lgkmcnt(0)
	ds_read_b128 v[16:19], v4
	ds_read_b128 v[20:23], v4 offset:1024
	ds_read_b128 v[24:27], v4 offset:2048
	ds_read_b128 v[28:31], v4 offset:3072
	ds_read_b128 v[32:35], v4 offset:4096
	ds_read_b128 v[36:39], v4 offset:5120
	ds_read_b128 v[40:43], v4 offset:6144
	ds_read_b128 v[44:47], v4 offset:7168
	s_waitcnt lgkmcnt(7)
	global_store_dwordx4 v5, v[16:19], s[40:41]
	s_add_u32 s40, s40, 0x4000
	s_addc_u32 s41, s41, 0
	s_waitcnt lgkmcnt(6)
	global_store_dwordx4 v5, v[20:23], s[40:41]
	s_add_u32 s40, s40, 0x4000
	s_addc_u32 s41, s41, 0
	s_waitcnt lgkmcnt(5)
	global_store_dwordx4 v5, v[24:27], s[40:41]
	s_add_u32 s40, s40, 0x4000
	s_addc_u32 s41, s41, 0
	s_waitcnt lgkmcnt(4)
	global_store_dwordx4 v5, v[28:31], s[40:41]
	s_add_u32 s40, s40, 0x4000
	s_addc_u32 s41, s41, 0
	s_waitcnt lgkmcnt(3)
	global_store_dwordx4 v5, v[32:35], s[40:41]
	s_add_u32 s40, s40, 0x4000
	s_addc_u32 s41, s41, 0
	s_waitcnt lgkmcnt(2)
	global_store_dwordx4 v5, v[36:39], s[40:41]
	s_add_u32 s40, s40, 0x4000
	s_addc_u32 s41, s41, 0
	s_waitcnt lgkmcnt(1)
	global_store_dwordx4 v5, v[40:43], s[40:41]
	s_add_u32 s40, s40, 0x4000
	s_addc_u32 s41, s41, 0
	s_waitcnt lgkmcnt(0)
	global_store_dwordx4 v5, v[44:47], s[40:41]
	s_mov_b32 s40, s61
	s_add_i32 s60, s60, s3
	s_cmpk_lt_i32 s60, 0x600
	s_waitcnt lgkmcnt(0)
	s_cbranch_scc0 .LBB0_479
